# v8 plus DMA issue balanced 4/4/4/4 per load segment in the P5, P7, P10 GEMM loops as in P2
# baseline (speedup 1.0000x reference)
; #define PG8_STAGE(bufoff, gbase, voff) do { _Pragma("unroll") for (int _i = 0; _i < 2; ++_i) \
;         __builtin_amdgcn_global_load_lds((const unsigned*)((const char*)(gbase) + (voff)[_i]), (PG8_LAS unsigned*)(lds + (bufoff) + ldsw + _i * 8192), 16, 0, 0); } while (0)
; #define PG8_LDA(dst, b, h) do { _Pragma("unroll") for (int m = 0; m < 4; ++m) _Pragma("unroll") for (int k = 0; k < 2; ++k) dst[m][k] = *(const PG8_LAS bf16x8*)(lds + PG8_SA(b, h) + aoff + m * 2048 + k * 1024); } while (0)
; #define PG8_LDB(dst, b, h) do { _Pragma("unroll") for (int n = 0; n < 2; ++n) _Pragma("unroll") for (int k = 0; k < 2; ++k) dst[n][k] = *(const PG8_LAS bf16x8*)(lds + PG8_SB(b, h) + boff + n * 2048 + k * 1024); } while (0)
; template <class Epi, class Sched, bool ALIGN_EPI = false, bool SP2 = false>
; __device__ __forceinline__ void gemm_phase(PG8_LAS unsigned char* lds, const Gemm g, const Sched& S, const Epi& E) {
;     ...
;         for (int t = 0; t < nt; t += 2) {
;             const bool last = (t == nt - 2);
;             const char* a1 = cA + (size_t)(t + 1) * kstep;
;             const char* a2 = last ? nA : cA + (size_t)(t + 2) * kstep; const char* b2 = last ? nB : cB + (size_t)(t + 2) * kstep;
;             const char* a3 = a2 + kstep; const char* b3 = b2 + kstep;
;             if (last && has_next) S.a_ready(nxt);
;             if constexpr (SP2) {
;             PG8_LDB(B0, 0, 0); PG8_LDB(B1, 0, 1); PG8_SCHED; PG8_LDA(At, 0, 0); PG8_STAGE(PG8_SA(1, 1), a1 + hstep, voffA);
;             PG8_WAIT_V(8); PG8_WAIT_L(0); PG8_BAR; PG8_MMA(0, 0, At, B0); PG8_MMA(0, 1, At, B1); PG8_BAR; PG8_SCHED;
;             PG8_LDA(At, 0, 1); PG8_STAGE(PG8_SB(0, 0), b2, voffB); PG8_STAGE(PG8_SB(0, 1), b2 + hstep, voffB); PG8_STAGE(PG8_SA(0, 0), a2, voffA);
;             PG8_WAIT_V(8); PG8_WAIT_L(0); PG8_BAR; PG8_MMA(1, 0, At, B0); PG8_MMA(1, 1, At, B1); PG8_BAR; PG8_SCHED;
;             PG8_LDB(B0, 1, 0); PG8_LDB(B1, 1, 1); PG8_SCHED; PG8_LDA(At, 1, 0); PG8_STAGE(PG8_SA(0, 1), a2 + hstep, voffA);
;             PG8_WAIT_V(8); PG8_WAIT_L(0); PG8_BAR; PG8_MMA(0, 0, At, B0); PG8_MMA(0, 1, At, B1); PG8_BAR; PG8_SCHED;
;             PG8_LDA(At, 1, 1); PG8_STAGE(PG8_SB(1, 0), b3, voffB); PG8_STAGE(PG8_SB(1, 1), b3 + hstep, voffB); PG8_STAGE(PG8_SA(1, 0), a3, voffA);
;             PG8_WAIT_V(8); PG8_WAIT_L(0); PG8_BAR; PG8_MMA(1, 0, At, B0); PG8_MMA(1, 1, At, B1); PG8_BAR; PG8_SCHED;
.LBB0_632:
	ds_read_b128 v[128:131], v163
	ds_read_b128 v[132:135], v163 offset:1024
	ds_read_b128 v[136:139], v163 offset:2048
	ds_read_b128 v[140:143], v163 offset:3072
	ds_read_b128 v[156:159], v164
	ds_read_b128 v[170:173], v164 offset:1024
	ds_read_b128 v[174:177], v164 offset:2048
	ds_read_b128 v[178:181], v164 offset:3072
	s_add_u32 s68, s28, 0xfff00000
	s_addc_u32 s69, s29, -1
	s_add_u32 s30, s28, 0xfff00080
	s_addc_u32 s31, s29, -1
	s_cmp_eq_u32 s66, 60
	s_cselect_b32 s35, s21, s31
	s_cselect_b32 s34, s62, s30
	s_cselect_b32 s31, s19, s65
	s_cselect_b32 s30, s63, s64
	v_lshl_add_u64 v[166:167], s[68:69], 0, v[148:149]
	s_mov_b32 m0, s55
	ds_read_b128 v[182:185], v165
	ds_read_b128 v[186:189], v165 offset:1024
	ds_read_b128 v[190:193], v165 offset:2048
	ds_read_b128 v[194:197], v165 offset:3072
	ds_read_b128 v[198:201], v165 offset:4096
	ds_read_b128 v[202:205], v165 offset:5120
	ds_read_b128 v[206:209], v165 offset:6144
	ds_read_b128 v[210:213], v165 offset:7168
	global_load_lds_dwordx4 v[166:167], off
	v_lshl_add_u64 v[166:167], s[68:69], 0, v[150:151]
	s_mov_b32 m0, s56
	s_nop 0
	global_load_lds_dwordx4 v[166:167], off
	v_lshl_add_u64 v[166:167], s[28:29], 0, v[148:149]
	s_add_i32 m0, s27, 0xc000
	s_nop 0
	global_load_lds_dwordx4 v[166:167], off
	v_lshl_add_u64 v[166:167], s[28:29], 0, v[150:151]
	s_add_i32 m0, s27, 0xe000
	s_nop 0
	global_load_lds_dwordx4 v[166:167], off
	s_waitcnt vmcnt(8)
	s_waitcnt lgkmcnt(0)
	s_barrier
	s_setprio 1
	s_waitcnt lgkmcnt(0)
	v_mfma_f32_16x16x32_bf16 v[124:127], v[128:131], v[182:185], v[124:127]
	v_mfma_f32_16x16x32_bf16 v[120:123], v[136:139], v[182:185], v[120:123]
	v_mfma_f32_16x16x32_bf16 v[112:115], v[128:131], v[190:193], v[112:115]
	v_mfma_f32_16x16x32_bf16 v[104:107], v[136:139], v[190:193], v[104:107]
	v_mfma_f32_16x16x32_bf16 v[96:99], v[128:131], v[198:201], v[96:99]
	v_mfma_f32_16x16x32_bf16 v[88:91], v[136:139], v[198:201], v[88:91]
	v_mfma_f32_16x16x32_bf16 v[80:83], v[128:131], v[206:209], v[80:83]
	v_mfma_f32_16x16x32_bf16 v[72:75], v[136:139], v[206:209], v[72:75]
	v_mfma_f32_16x16x32_bf16 v[124:127], v[132:135], v[186:189], v[124:127]
	v_mfma_f32_16x16x32_bf16 v[120:123], v[140:143], v[186:189], v[120:123]
	v_mfma_f32_16x16x32_bf16 v[112:115], v[132:135], v[194:197], v[112:115]
	v_mfma_f32_16x16x32_bf16 v[104:107], v[140:143], v[194:197], v[104:107]
	v_mfma_f32_16x16x32_bf16 v[96:99], v[132:135], v[202:205], v[96:99]
	v_mfma_f32_16x16x32_bf16 v[88:91], v[140:143], v[202:205], v[88:91]
	v_mfma_f32_16x16x32_bf16 v[80:83], v[132:135], v[210:213], v[80:83]
	v_mfma_f32_16x16x32_bf16 v[72:75], v[140:143], v[210:213], v[72:75]
	s_setprio 0
	s_setprio 1
	v_mfma_f32_16x16x32_bf16 v[116:119], v[156:159], v[182:185], v[116:119]
	v_mfma_f32_16x16x32_bf16 v[108:111], v[174:177], v[182:185], v[108:111]
	v_mfma_f32_16x16x32_bf16 v[100:103], v[156:159], v[190:193], v[100:103]
	v_mfma_f32_16x16x32_bf16 v[92:95], v[174:177], v[190:193], v[92:95]
	v_mfma_f32_16x16x32_bf16 v[84:87], v[156:159], v[198:201], v[84:87]
	v_mfma_f32_16x16x32_bf16 v[76:79], v[174:177], v[198:201], v[76:79]
	v_mfma_f32_16x16x32_bf16 v[68:71], v[156:159], v[206:209], v[68:71]
	v_mfma_f32_16x16x32_bf16 v[64:67], v[174:177], v[206:209], v[64:67]
	v_mfma_f32_16x16x32_bf16 v[116:119], v[170:173], v[186:189], v[116:119]
	v_mfma_f32_16x16x32_bf16 v[108:111], v[178:181], v[186:189], v[108:111]
	v_mfma_f32_16x16x32_bf16 v[100:103], v[170:173], v[194:197], v[100:103]
	v_mfma_f32_16x16x32_bf16 v[92:95], v[178:181], v[194:197], v[92:95]
	v_mfma_f32_16x16x32_bf16 v[84:87], v[170:173], v[202:205], v[84:87]
	v_mfma_f32_16x16x32_bf16 v[76:79], v[178:181], v[202:205], v[76:79]
	v_mfma_f32_16x16x32_bf16 v[68:71], v[170:173], v[210:213], v[68:71]
	v_mfma_f32_16x16x32_bf16 v[64:67], v[178:181], v[210:213], v[64:67]
	s_setprio 0
	s_barrier
	s_add_i32 s67, s59, s46
	v_lshl_add_u64 v[166:167], s[30:31], 0, v[144:145]
	s_mov_b32 m0, s67
	ds_read_b128 v[182:185], v165 offset:16384
	ds_read_b128 v[186:189], v165 offset:17408
	ds_read_b128 v[190:193], v165 offset:18432
	ds_read_b128 v[194:197], v165 offset:19456
	ds_read_b128 v[198:201], v165 offset:20480
	ds_read_b128 v[202:205], v165 offset:21504
	ds_read_b128 v[206:209], v165 offset:22528
	ds_read_b128 v[210:213], v165 offset:23552
	global_load_lds_dwordx4 v[166:167], off
	s_add_i32 m0, s67, 0x2000
	s_add_u32 s68, s30, 0x100000
	v_lshl_add_u64 v[214:215], s[30:31], 0, v[146:147]
	s_addc_u32 s69, s31, 0
	s_add_i32 s67, s60, s46
	global_load_lds_dwordx4 v[214:215], off
	v_lshl_add_u64 v[216:217], s[68:69], 0, v[144:145]
	s_mov_b32 m0, s67
	v_lshl_add_u64 v[218:219], s[34:35], 0, v[146:147]
	global_load_lds_dwordx4 v[216:217], off
	v_lshl_add_u64 v[216:217], s[68:69], 0, v[146:147]
	s_add_i32 m0, s67, 0x2000
	s_nop 0
	global_load_lds_dwordx4 v[216:217], off
	s_waitcnt vmcnt(6)
	s_waitcnt lgkmcnt(0)
	s_barrier
; #define PG8_STAGE(bufoff, gbase, voff) do { _Pragma("unroll") for (int _i = 0; _i < 2; ++_i) \
;         __builtin_amdgcn_global_load_lds((const unsigned*)((const char*)(gbase) + (voff)[_i]), (PG8_LAS unsigned*)(lds + (bufoff) + ldsw + _i * 8192), 16, 0, 0); } while (0)
; #define PG8_LDA(dst, b, h) do { _Pragma("unroll") for (int m = 0; m < 4; ++m) _Pragma("unroll") for (int k = 0; k < 2; ++k) dst[m][k] = *(const PG8_LAS bf16x8*)(lds + PG8_SA(b, h) + aoff + m * 2048 + k * 1024); } while (0)
; #define PG8_LDB(dst, b, h) do { _Pragma("unroll") for (int n = 0; n < 2; ++n) _Pragma("unroll") for (int k = 0; k < 2; ++k) dst[n][k] = *(const PG8_LAS bf16x8*)(lds + PG8_SB(b, h) + boff + n * 2048 + k * 1024); } while (0)
; #define PG8_MMA(ai, bj, At, Bt) do { __builtin_amdgcn_s_setprio(1); _Pragma("unroll") for (int m = 0; m < 4; ++m) _Pragma("unroll") for (int n = 0; n < 2; ++n) _Pragma("unroll") for (int k = 0; k < 2; ++k) \
;         acc[ai][bj][m][n] = __builtin_amdgcn_mfma_f32_16x16x32_bf16(Bt[n][k], At[m][k], acc[ai][bj][m][n], 0, 0, 0); __builtin_amdgcn_s_setprio(0); } while (0)
; #define PG8_WAIT_V(n) asm volatile("s_waitcnt vmcnt(" #n ")" ::: "memory")
; template <class Epi, class Sched, bool ALIGN_EPI = false, bool SP2 = false>
; __device__ __forceinline__ void gemm_phase(PG8_LAS unsigned char* lds, const Gemm g, const Sched& S, const Epi& E) {
;     ...
;             PG8_LDB(B0, 0, 0); PG8_LDB(B1, 0, 1); PG8_SCHED; PG8_LDA(At, 0, 0); PG8_STAGE(PG8_SA(1, 1), a1 + hstep, voffA);
;             PG8_WAIT_V(8); PG8_WAIT_L(0); PG8_BAR; PG8_MMA(0, 0, At, B0); PG8_MMA(0, 1, At, B1); PG8_BAR; PG8_SCHED;
;             PG8_LDA(At, 0, 1); PG8_STAGE(PG8_SB(0, 0), b2, voffB); PG8_STAGE(PG8_SB(0, 1), b2 + hstep, voffB); PG8_STAGE(PG8_SA(0, 0), a2, voffA);
;             PG8_WAIT_V(8); PG8_WAIT_L(0); PG8_BAR; PG8_MMA(1, 0, At, B0); PG8_MMA(1, 1, At, B1); PG8_BAR; PG8_SCHED;
;             PG8_LDB(B0, 1, 0); PG8_LDB(B1, 1, 1); PG8_SCHED; PG8_LDA(At, 1, 0); PG8_STAGE(PG8_SA(0, 1), a2 + hstep, voffA);
;             PG8_WAIT_V(8); PG8_WAIT_L(0); PG8_BAR; PG8_MMA(0, 0, At, B0); PG8_MMA(0, 1, At, B1); PG8_BAR; PG8_SCHED;
;             PG8_LDA(At, 1, 1); PG8_STAGE(PG8_SB(1, 0), b3, voffB); PG8_STAGE(PG8_SB(1, 1), b3 + hstep, voffB); PG8_STAGE(PG8_SA(1, 0), a3, voffA);
;             PG8_WAIT_V(8); PG8_WAIT_L(0); PG8_BAR; PG8_MMA(1, 0, At, B0); PG8_MMA(1, 1, At, B1); PG8_BAR; PG8_SCHED;
	s_setprio 1
	s_waitcnt lgkmcnt(0)
	v_mfma_f32_16x16x32_bf16 v[60:63], v[128:131], v[182:185], v[60:63]
	v_mfma_f32_16x16x32_bf16 v[56:59], v[136:139], v[182:185], v[56:59]
	v_mfma_f32_16x16x32_bf16 v[48:51], v[128:131], v[190:193], v[48:51]
	v_mfma_f32_16x16x32_bf16 v[40:43], v[136:139], v[190:193], v[40:43]
	v_mfma_f32_16x16x32_bf16 v[32:35], v[128:131], v[198:201], v[32:35]
	v_mfma_f32_16x16x32_bf16 v[24:27], v[136:139], v[198:201], v[24:27]
	v_mfma_f32_16x16x32_bf16 v[16:19], v[128:131], v[206:209], v[16:19]
	v_mfma_f32_16x16x32_bf16 v[8:11], v[136:139], v[206:209], v[8:11]
	v_mfma_f32_16x16x32_bf16 v[60:63], v[132:135], v[186:189], v[60:63]
	v_mfma_f32_16x16x32_bf16 v[56:59], v[140:143], v[186:189], v[56:59]
	v_mfma_f32_16x16x32_bf16 v[48:51], v[132:135], v[194:197], v[48:51]
	v_mfma_f32_16x16x32_bf16 v[40:43], v[140:143], v[194:197], v[40:43]
	v_mfma_f32_16x16x32_bf16 v[32:35], v[132:135], v[202:205], v[32:35]
	v_mfma_f32_16x16x32_bf16 v[24:27], v[140:143], v[202:205], v[24:27]
	v_mfma_f32_16x16x32_bf16 v[16:19], v[132:135], v[210:213], v[16:19]
	v_mfma_f32_16x16x32_bf16 v[8:11], v[140:143], v[210:213], v[8:11]
	s_setprio 0
	s_setprio 1
	v_mfma_f32_16x16x32_bf16 v[52:55], v[156:159], v[182:185], v[52:55]
	v_mfma_f32_16x16x32_bf16 v[44:47], v[174:177], v[182:185], v[44:47]
	v_mfma_f32_16x16x32_bf16 v[36:39], v[156:159], v[190:193], v[36:39]
	v_mfma_f32_16x16x32_bf16 v[28:31], v[174:177], v[190:193], v[28:31]
	v_mfma_f32_16x16x32_bf16 v[20:23], v[156:159], v[198:201], v[20:23]
	v_mfma_f32_16x16x32_bf16 v[12:15], v[174:177], v[198:201], v[12:15]
	v_mfma_f32_16x16x32_bf16 v[4:7], v[156:159], v[206:209], v[4:7]
	v_mfma_f32_16x16x32_bf16 v[0:3], v[174:177], v[206:209], v[0:3]
	v_mfma_f32_16x16x32_bf16 v[52:55], v[170:173], v[186:189], v[52:55]
	v_mfma_f32_16x16x32_bf16 v[44:47], v[178:181], v[186:189], v[44:47]
	v_mfma_f32_16x16x32_bf16 v[36:39], v[170:173], v[194:197], v[36:39]
	v_mfma_f32_16x16x32_bf16 v[28:31], v[178:181], v[194:197], v[28:31]
	v_mfma_f32_16x16x32_bf16 v[20:23], v[170:173], v[202:205], v[20:23]
	v_mfma_f32_16x16x32_bf16 v[12:15], v[178:181], v[202:205], v[12:15]
	v_mfma_f32_16x16x32_bf16 v[4:7], v[170:173], v[210:213], v[4:7]
	v_mfma_f32_16x16x32_bf16 v[0:3], v[178:181], v[210:213], v[0:3]
	s_setprio 0
	s_barrier
	s_add_i32 s67, 0, 0x18000
	s_add_i32 s68, 0, 0x1c000
	v_add_u32_e32 v140, s67, v161
	v_add_u32_e32 v169, s68, v161
	ds_read_b128 v[128:131], v140
	ds_read_b128 v[132:135], v140 offset:1024
	ds_read_b128 v[136:139], v140 offset:2048
	ds_read_b128 v[140:143], v140 offset:3072
	ds_read_b128 v[156:159], v169
	ds_read_b128 v[170:173], v169 offset:1024
	ds_read_b128 v[174:177], v169 offset:2048
	ds_read_b128 v[178:181], v169 offset:3072
	v_lshl_add_u64 v[216:217], s[34:35], 0, v[144:145]
	s_add_u32 s34, s34, 0x100000
	s_addc_u32 s35, s35, 0
	s_mov_b32 m0, s27
	v_lshl_add_u64 v[220:221], s[34:35], 0, v[144:145]
	ds_read_b128 v[182:185], v165 offset:32768
	ds_read_b128 v[186:189], v165 offset:33792
	ds_read_b128 v[190:193], v165 offset:34816
	ds_read_b128 v[194:197], v165 offset:35840
	ds_read_b128 v[198:201], v165 offset:36864
	ds_read_b128 v[202:205], v165 offset:37888
	ds_read_b128 v[206:209], v165 offset:38912
	ds_read_b128 v[210:213], v165 offset:39936
	global_load_lds_dwordx4 v[216:217], off
	s_mov_b32 m0, s47
	s_nop 0
	global_load_lds_dwordx4 v[218:219], off
	s_mov_b32 m0, s48
	s_nop 0
	global_load_lds_dwordx4 v[220:221], off
	v_lshl_add_u64 v[220:221], s[34:35], 0, v[146:147]
	s_mov_b32 m0, s49
	s_nop 0
	global_load_lds_dwordx4 v[220:221], off
	s_waitcnt vmcnt(8)
	s_waitcnt lgkmcnt(0)
	s_barrier
; #define PG8_STAGE(bufoff, gbase, voff) do { _Pragma("unroll") for (int _i = 0; _i < 2; ++_i) \
;         __builtin_amdgcn_global_load_lds((const unsigned*)((const char*)(gbase) + (voff)[_i]), (PG8_LAS unsigned*)(lds + (bufoff) + ldsw + _i * 8192), 16, 0, 0); } while (0)
; #define PG8_LDA(dst, b, h) do { _Pragma("unroll") for (int m = 0; m < 4; ++m) _Pragma("unroll") for (int k = 0; k < 2; ++k) dst[m][k] = *(const PG8_LAS bf16x8*)(lds + PG8_SA(b, h) + aoff + m * 2048 + k * 1024); } while (0)
; #define PG8_LDB(dst, b, h) do { _Pragma("unroll") for (int n = 0; n < 2; ++n) _Pragma("unroll") for (int k = 0; k < 2; ++k) dst[n][k] = *(const PG8_LAS bf16x8*)(lds + PG8_SB(b, h) + boff + n * 2048 + k * 1024); } while (0)
; template <class Epi, class Sched, bool ALIGN_EPI = false, bool SP2 = false>
; __device__ __forceinline__ void gemm_phase(PG8_LAS unsigned char* lds, const Gemm g, const Sched& S, const Epi& E) {
;     ...
;         for (int t = 0; t < nt; t += 2) {
;             const bool last = (t == nt - 2);
;             const char* a1 = cA + (size_t)(t + 1) * kstep;
;             const char* a2 = last ? nA : cA + (size_t)(t + 2) * kstep; const char* b2 = last ? nB : cB + (size_t)(t + 2) * kstep;
;             const char* a3 = a2 + kstep; const char* b3 = b2 + kstep;
;             if (last && has_next) S.a_ready(nxt);
;             if constexpr (SP2) {
;             PG8_LDB(B0, 0, 0); PG8_LDB(B1, 0, 1); PG8_SCHED; PG8_LDA(At, 0, 0); PG8_STAGE(PG8_SA(1, 1), a1 + hstep, voffA);
;             PG8_WAIT_V(8); PG8_WAIT_L(0); PG8_BAR; PG8_MMA(0, 0, At, B0); PG8_MMA(0, 1, At, B1); PG8_BAR; PG8_SCHED;
;             PG8_LDA(At, 0, 1); PG8_STAGE(PG8_SB(0, 0), b2, voffB); PG8_STAGE(PG8_SB(0, 1), b2 + hstep, voffB); PG8_STAGE(PG8_SA(0, 0), a2, voffA);
;             PG8_WAIT_V(8); PG8_WAIT_L(0); PG8_BAR; PG8_MMA(1, 0, At, B0); PG8_MMA(1, 1, At, B1); PG8_BAR; PG8_SCHED;
;             PG8_LDB(B0, 1, 0); PG8_LDB(B1, 1, 1); PG8_SCHED; PG8_LDA(At, 1, 0); PG8_STAGE(PG8_SA(0, 1), a2 + hstep, voffA);
;             PG8_WAIT_V(8); PG8_WAIT_L(0); PG8_BAR; PG8_MMA(0, 0, At, B0); PG8_MMA(0, 1, At, B1); PG8_BAR; PG8_SCHED;
;             PG8_LDA(At, 1, 1); PG8_STAGE(PG8_SB(1, 0), b3, voffB); PG8_STAGE(PG8_SB(1, 1), b3 + hstep, voffB); PG8_STAGE(PG8_SA(1, 0), a3, voffA);
;             PG8_WAIT_V(8); PG8_WAIT_L(0); PG8_BAR; PG8_MMA(1, 0, At, B0); PG8_MMA(1, 1, At, B1); PG8_BAR; PG8_SCHED;
	s_setprio 1
	s_waitcnt lgkmcnt(0)
	v_mfma_f32_16x16x32_bf16 v[124:127], v[128:131], v[182:185], v[124:127]
	v_mfma_f32_16x16x32_bf16 v[120:123], v[136:139], v[182:185], v[120:123]
	v_mfma_f32_16x16x32_bf16 v[112:115], v[128:131], v[190:193], v[112:115]
	v_mfma_f32_16x16x32_bf16 v[104:107], v[136:139], v[190:193], v[104:107]
	v_mfma_f32_16x16x32_bf16 v[96:99], v[128:131], v[198:201], v[96:99]
	v_mfma_f32_16x16x32_bf16 v[88:91], v[136:139], v[198:201], v[88:91]
	v_mfma_f32_16x16x32_bf16 v[80:83], v[128:131], v[206:209], v[80:83]
	v_mfma_f32_16x16x32_bf16 v[72:75], v[136:139], v[206:209], v[72:75]
	v_mfma_f32_16x16x32_bf16 v[124:127], v[132:135], v[186:189], v[124:127]
	v_mfma_f32_16x16x32_bf16 v[120:123], v[140:143], v[186:189], v[120:123]
	v_mfma_f32_16x16x32_bf16 v[112:115], v[132:135], v[194:197], v[112:115]
	v_mfma_f32_16x16x32_bf16 v[104:107], v[140:143], v[194:197], v[104:107]
	v_mfma_f32_16x16x32_bf16 v[96:99], v[132:135], v[202:205], v[96:99]
	v_mfma_f32_16x16x32_bf16 v[88:91], v[140:143], v[202:205], v[88:91]
	v_mfma_f32_16x16x32_bf16 v[80:83], v[132:135], v[210:213], v[80:83]
	v_mfma_f32_16x16x32_bf16 v[72:75], v[140:143], v[210:213], v[72:75]
	s_setprio 0
	s_setprio 1
	v_mfma_f32_16x16x32_bf16 v[116:119], v[156:159], v[182:185], v[116:119]
	v_mfma_f32_16x16x32_bf16 v[108:111], v[174:177], v[182:185], v[108:111]
	v_mfma_f32_16x16x32_bf16 v[100:103], v[156:159], v[190:193], v[100:103]
	v_mfma_f32_16x16x32_bf16 v[92:95], v[174:177], v[190:193], v[92:95]
	v_mfma_f32_16x16x32_bf16 v[84:87], v[156:159], v[198:201], v[84:87]
	v_mfma_f32_16x16x32_bf16 v[76:79], v[174:177], v[198:201], v[76:79]
	v_mfma_f32_16x16x32_bf16 v[68:71], v[156:159], v[206:209], v[68:71]
	v_mfma_f32_16x16x32_bf16 v[64:67], v[174:177], v[206:209], v[64:67]
	v_mfma_f32_16x16x32_bf16 v[116:119], v[170:173], v[186:189], v[116:119]
	v_mfma_f32_16x16x32_bf16 v[108:111], v[178:181], v[186:189], v[108:111]
	v_mfma_f32_16x16x32_bf16 v[100:103], v[170:173], v[194:197], v[100:103]
	v_mfma_f32_16x16x32_bf16 v[92:95], v[178:181], v[194:197], v[92:95]
	v_mfma_f32_16x16x32_bf16 v[84:87], v[170:173], v[202:205], v[84:87]
	v_mfma_f32_16x16x32_bf16 v[76:79], v[178:181], v[202:205], v[76:79]
	v_mfma_f32_16x16x32_bf16 v[68:71], v[170:173], v[210:213], v[68:71]
	v_mfma_f32_16x16x32_bf16 v[64:67], v[178:181], v[210:213], v[64:67]
	s_setprio 0
	s_barrier
	s_add_i32 s34, s67, s46
	v_lshl_add_u64 v[166:167], v[166:167], 0, s[6:7]
	s_mov_b32 m0, s34
	ds_read_b128 v[182:185], v165 offset:49152
	ds_read_b128 v[186:189], v165 offset:50176
	ds_read_b128 v[190:193], v165 offset:51200
	ds_read_b128 v[194:197], v165 offset:52224
	ds_read_b128 v[198:201], v165 offset:53248
	ds_read_b128 v[202:205], v165 offset:54272
	ds_read_b128 v[206:209], v165 offset:55296
	ds_read_b128 v[210:213], v165 offset:56320
	global_load_lds_dwordx4 v[166:167], off
	s_add_i32 m0, s34, 0x2000
	s_add_u32 s30, s30, 0x100080
	v_lshl_add_u64 v[166:167], v[214:215], 0, s[6:7]
	s_addc_u32 s31, s31, 0
	s_add_i32 s34, s68, s46
	global_load_lds_dwordx4 v[166:167], off
	v_lshl_add_u64 v[166:167], s[30:31], 0, v[144:145]
	s_mov_b32 m0, s34
	s_nop 0
	global_load_lds_dwordx4 v[166:167], off
	v_lshl_add_u64 v[166:167], s[30:31], 0, v[146:147]
	s_add_i32 m0, s34, 0x2000
	s_nop 0
	global_load_lds_dwordx4 v[166:167], off
	s_waitcnt vmcnt(6)
	s_waitcnt lgkmcnt(0)
	s_barrier
	s_setprio 1
	s_waitcnt lgkmcnt(0)
	v_mfma_f32_16x16x32_bf16 v[60:63], v[128:131], v[182:185], v[60:63]
	v_mfma_f32_16x16x32_bf16 v[56:59], v[136:139], v[182:185], v[56:59]
	v_mfma_f32_16x16x32_bf16 v[48:51], v[128:131], v[190:193], v[48:51]
	v_mfma_f32_16x16x32_bf16 v[40:43], v[136:139], v[190:193], v[40:43]
	v_mfma_f32_16x16x32_bf16 v[32:35], v[128:131], v[198:201], v[32:35]
	v_mfma_f32_16x16x32_bf16 v[24:27], v[136:139], v[198:201], v[24:27]
	v_mfma_f32_16x16x32_bf16 v[16:19], v[128:131], v[206:209], v[16:19]
	v_mfma_f32_16x16x32_bf16 v[8:11], v[136:139], v[206:209], v[8:11]
	v_mfma_f32_16x16x32_bf16 v[60:63], v[132:135], v[186:189], v[60:63]
	v_mfma_f32_16x16x32_bf16 v[56:59], v[140:143], v[186:189], v[56:59]
	v_mfma_f32_16x16x32_bf16 v[48:51], v[132:135], v[194:197], v[48:51]
	v_mfma_f32_16x16x32_bf16 v[40:43], v[140:143], v[194:197], v[40:43]
	v_mfma_f32_16x16x32_bf16 v[32:35], v[132:135], v[202:205], v[32:35]
	v_mfma_f32_16x16x32_bf16 v[24:27], v[140:143], v[202:205], v[24:27]
	v_mfma_f32_16x16x32_bf16 v[16:19], v[132:135], v[210:213], v[16:19]
	v_mfma_f32_16x16x32_bf16 v[8:11], v[140:143], v[210:213], v[8:11]
	s_setprio 0
	s_setprio 1
	v_mfma_f32_16x16x32_bf16 v[52:55], v[156:159], v[182:185], v[52:55]
	v_mfma_f32_16x16x32_bf16 v[44:47], v[174:177], v[182:185], v[44:47]
	v_mfma_f32_16x16x32_bf16 v[36:39], v[156:159], v[190:193], v[36:39]
	v_mfma_f32_16x16x32_bf16 v[28:31], v[174:177], v[190:193], v[28:31]
	v_mfma_f32_16x16x32_bf16 v[20:23], v[156:159], v[198:201], v[20:23]
	v_mfma_f32_16x16x32_bf16 v[12:15], v[174:177], v[198:201], v[12:15]
	v_mfma_f32_16x16x32_bf16 v[4:7], v[156:159], v[206:209], v[4:7]
	v_mfma_f32_16x16x32_bf16 v[0:3], v[174:177], v[206:209], v[0:3]
	v_mfma_f32_16x16x32_bf16 v[52:55], v[170:173], v[186:189], v[52:55]
	v_mfma_f32_16x16x32_bf16 v[44:47], v[178:181], v[186:189], v[44:47]
	v_mfma_f32_16x16x32_bf16 v[36:39], v[170:173], v[194:197], v[36:39]
	v_mfma_f32_16x16x32_bf16 v[28:31], v[178:181], v[194:197], v[28:31]
	v_mfma_f32_16x16x32_bf16 v[20:23], v[170:173], v[202:205], v[20:23]
	v_mfma_f32_16x16x32_bf16 v[12:15], v[178:181], v[202:205], v[12:15]
	v_mfma_f32_16x16x32_bf16 v[4:7], v[170:173], v[210:213], v[4:7]
	v_mfma_f32_16x16x32_bf16 v[0:3], v[178:181], v[210:213], v[0:3]
	s_setprio 0
	s_barrier
	s_add_i32 s66, s66, 2
	s_add_u32 s28, s28, 0x100
	s_addc_u32 s29, s29, 0
	s_add_u32 s64, s64, 0x100
	s_addc_u32 s65, s65, 0
	s_cmp_gt_u32 s66, 61
	s_cbranch_scc0 .LBB0_632
	s_and_b64 vcc, exec, s[8:9]
	s_cbranch_vccz .LBB0_635
	s_barrier

; #define PG8_STAGE(bufoff, gbase, voff) do { _Pragma("unroll") for (int _i = 0; _i < 2; ++_i) \
;         __builtin_amdgcn_global_load_lds((const unsigned*)((const char*)(gbase) + (voff)[_i]), (PG8_LAS unsigned*)(lds + (bufoff) + ldsw + _i * 8192), 16, 0, 0); } while (0)
; #define PG8_LDA(dst, b, h) do { _Pragma("unroll") for (int m = 0; m < 4; ++m) _Pragma("unroll") for (int k = 0; k < 2; ++k) dst[m][k] = *(const PG8_LAS bf16x8*)(lds + PG8_SA(b, h) + aoff + m * 2048 + k * 1024); } while (0)
; #define PG8_LDB(dst, b, h) do { _Pragma("unroll") for (int n = 0; n < 2; ++n) _Pragma("unroll") for (int k = 0; k < 2; ++k) dst[n][k] = *(const PG8_LAS bf16x8*)(lds + PG8_SB(b, h) + boff + n * 2048 + k * 1024); } while (0)
; template <class Epi, class Sched, bool ALIGN_EPI = false, bool SP2 = false>
; __device__ __forceinline__ void gemm_phase(PG8_LAS unsigned char* lds, const Gemm g, const Sched& S, const Epi& E) {
;     ...
;         for (int t = 0; t < nt; t += 2) {
;             const bool last = (t == nt - 2);
;             const char* a1 = cA + (size_t)(t + 1) * kstep;
;             const char* a2 = last ? nA : cA + (size_t)(t + 2) * kstep; const char* b2 = last ? nB : cB + (size_t)(t + 2) * kstep;
;             const char* a3 = a2 + kstep; const char* b3 = b2 + kstep;
;             if (last && has_next) S.a_ready(nxt);
;             if constexpr (SP2) {
;             PG8_LDB(B0, 0, 0); PG8_LDB(B1, 0, 1); PG8_SCHED; PG8_LDA(At, 0, 0); PG8_STAGE(PG8_SA(1, 1), a1 + hstep, voffA);
;             PG8_WAIT_V(8); PG8_WAIT_L(0); PG8_BAR; PG8_MMA(0, 0, At, B0); PG8_MMA(0, 1, At, B1); PG8_BAR; PG8_SCHED;
;             PG8_LDA(At, 0, 1); PG8_STAGE(PG8_SB(0, 0), b2, voffB); PG8_STAGE(PG8_SB(0, 1), b2 + hstep, voffB); PG8_STAGE(PG8_SA(0, 0), a2, voffA);
;             PG8_WAIT_V(8); PG8_WAIT_L(0); PG8_BAR; PG8_MMA(1, 0, At, B0); PG8_MMA(1, 1, At, B1); PG8_BAR; PG8_SCHED;
;             PG8_LDB(B0, 1, 0); PG8_LDB(B1, 1, 1); PG8_SCHED; PG8_LDA(At, 1, 0); PG8_STAGE(PG8_SA(0, 1), a2 + hstep, voffA);
;             PG8_WAIT_V(8); PG8_WAIT_L(0); PG8_BAR; PG8_MMA(0, 0, At, B0); PG8_MMA(0, 1, At, B1); PG8_BAR; PG8_SCHED;
;             PG8_LDA(At, 1, 1); PG8_STAGE(PG8_SB(1, 0), b3, voffB); PG8_STAGE(PG8_SB(1, 1), b3 + hstep, voffB); PG8_STAGE(PG8_SA(1, 0), a3, voffA);
;             PG8_WAIT_V(8); PG8_WAIT_L(0); PG8_BAR; PG8_MMA(1, 0, At, B0); PG8_MMA(1, 1, At, B1); PG8_BAR; PG8_SCHED;
.LBB0_766:
	ds_read_b128 v[128:131], v165
	ds_read_b128 v[156:159], v165 offset:1024
	ds_read_b128 v[160:163], v165 offset:2048
	ds_read_b128 v[170:173], v165 offset:3072
	ds_read_b128 v[174:177], v166
	ds_read_b128 v[178:181], v166 offset:1024
	ds_read_b128 v[182:185], v166 offset:2048
	ds_read_b128 v[186:189], v166 offset:3072
	s_add_u32 s82, s48, 0xfff80000
	s_addc_u32 s83, s49, -1
	s_add_u32 s50, s48, 0xfff80080
	s_addc_u32 s51, s49, -1
	s_cmp_eq_u32 s81, 28
	s_cselect_b32 s53, s33, s51
	s_cselect_b32 s52, s35, s50
	s_cselect_b32 s51, s31, s77
	s_cselect_b32 s50, s37, s76
	v_lshl_add_u64 v[222:223], s[82:83], 0, v[148:149]
	s_mov_b32 m0, s61
	ds_read_b128 v[190:193], v167
	ds_read_b128 v[194:197], v167 offset:1024
	ds_read_b128 v[198:201], v167 offset:2048
	ds_read_b128 v[202:205], v167 offset:3072
	ds_read_b128 v[206:209], v167 offset:4096
	ds_read_b128 v[210:213], v167 offset:5120
	ds_read_b128 v[214:217], v167 offset:6144
	ds_read_b128 v[218:221], v167 offset:7168
	global_load_lds_dwordx4 v[222:223], off
	v_lshl_add_u64 v[222:223], s[82:83], 0, v[150:151]
	s_mov_b32 m0, s62
	s_nop 0
	global_load_lds_dwordx4 v[222:223], off
	v_lshl_add_u64 v[222:223], s[48:49], 0, v[148:149]
	s_add_i32 m0, s47, 0xc000
	s_nop 0
	global_load_lds_dwordx4 v[222:223], off
	v_lshl_add_u64 v[222:223], s[48:49], 0, v[150:151]
	s_add_i32 m0, s47, 0xe000
	s_nop 0
	global_load_lds_dwordx4 v[222:223], off
	s_waitcnt vmcnt(8)
	s_waitcnt lgkmcnt(0)
	s_barrier
	s_setprio 1
	s_waitcnt lgkmcnt(0)
	v_mfma_f32_16x16x32_bf16 v[124:127], v[128:131], v[190:193], v[124:127]
	v_mfma_f32_16x16x32_bf16 v[120:123], v[160:163], v[190:193], v[120:123]
	v_mfma_f32_16x16x32_bf16 v[108:111], v[128:131], v[198:201], v[108:111]
	v_mfma_f32_16x16x32_bf16 v[104:107], v[160:163], v[198:201], v[104:107]
	v_mfma_f32_16x16x32_bf16 v[92:95], v[128:131], v[206:209], v[92:95]
	v_mfma_f32_16x16x32_bf16 v[88:91], v[160:163], v[206:209], v[88:91]
	v_mfma_f32_16x16x32_bf16 v[76:79], v[128:131], v[214:217], v[76:79]
	v_mfma_f32_16x16x32_bf16 v[72:75], v[160:163], v[214:217], v[72:75]
	v_mfma_f32_16x16x32_bf16 v[124:127], v[156:159], v[194:197], v[124:127]
	v_mfma_f32_16x16x32_bf16 v[120:123], v[170:173], v[194:197], v[120:123]
	v_mfma_f32_16x16x32_bf16 v[108:111], v[156:159], v[202:205], v[108:111]
	v_mfma_f32_16x16x32_bf16 v[104:107], v[170:173], v[202:205], v[104:107]
	v_mfma_f32_16x16x32_bf16 v[92:95], v[156:159], v[210:213], v[92:95]
	v_mfma_f32_16x16x32_bf16 v[88:91], v[170:173], v[210:213], v[88:91]
	v_mfma_f32_16x16x32_bf16 v[76:79], v[156:159], v[218:221], v[76:79]
	v_mfma_f32_16x16x32_bf16 v[72:75], v[170:173], v[218:221], v[72:75]
	s_setprio 0
	s_setprio 1
	v_mfma_f32_16x16x32_bf16 v[116:119], v[174:177], v[190:193], v[116:119]
	v_mfma_f32_16x16x32_bf16 v[112:115], v[182:185], v[190:193], v[112:115]
	v_mfma_f32_16x16x32_bf16 v[100:103], v[174:177], v[198:201], v[100:103]
	v_mfma_f32_16x16x32_bf16 v[96:99], v[182:185], v[198:201], v[96:99]
	v_mfma_f32_16x16x32_bf16 v[84:87], v[174:177], v[206:209], v[84:87]
	v_mfma_f32_16x16x32_bf16 v[80:83], v[182:185], v[206:209], v[80:83]
	v_mfma_f32_16x16x32_bf16 v[68:71], v[174:177], v[214:217], v[68:71]
	v_mfma_f32_16x16x32_bf16 v[64:67], v[182:185], v[214:217], v[64:67]
	v_mfma_f32_16x16x32_bf16 v[116:119], v[178:181], v[194:197], v[116:119]
	v_mfma_f32_16x16x32_bf16 v[112:115], v[186:189], v[194:197], v[112:115]
	v_mfma_f32_16x16x32_bf16 v[100:103], v[178:181], v[202:205], v[100:103]
	v_mfma_f32_16x16x32_bf16 v[96:99], v[186:189], v[202:205], v[96:99]
	v_mfma_f32_16x16x32_bf16 v[84:87], v[178:181], v[210:213], v[84:87]
	v_mfma_f32_16x16x32_bf16 v[80:83], v[186:189], v[210:213], v[80:83]
	v_mfma_f32_16x16x32_bf16 v[68:71], v[178:181], v[218:221], v[68:71]
	v_mfma_f32_16x16x32_bf16 v[64:67], v[186:189], v[218:221], v[64:67]
	s_setprio 0
	s_barrier
	s_add_i32 s82, s66, s56
	v_lshl_add_u64 v[222:223], s[50:51], 0, v[134:135]
	s_mov_b32 m0, s82
	ds_read_b128 v[190:193], v167 offset:16384
	ds_read_b128 v[194:197], v167 offset:17408
	ds_read_b128 v[198:201], v167 offset:18432
	ds_read_b128 v[202:205], v167 offset:19456
	ds_read_b128 v[206:209], v167 offset:20480
	ds_read_b128 v[210:213], v167 offset:21504
	ds_read_b128 v[214:217], v167 offset:22528
	ds_read_b128 v[218:221], v167 offset:23552
	global_load_lds_dwordx4 v[222:223], off
	s_add_i32 m0, s82, 0x2000
	s_add_u32 s82, s50, 0x80000
	v_lshl_add_u64 v[224:225], s[50:51], 0, v[138:139]
	s_addc_u32 s83, s51, 0
	s_add_i32 s84, s67, s56
	global_load_lds_dwordx4 v[224:225], off
	v_lshl_add_u64 v[226:227], s[82:83], 0, v[134:135]
	s_mov_b32 m0, s84
	v_lshl_add_u64 v[228:229], s[52:53], 0, v[136:137]
	global_load_lds_dwordx4 v[226:227], off
	v_lshl_add_u64 v[226:227], s[82:83], 0, v[138:139]
	s_add_i32 m0, s84, 0x2000
	s_nop 0
	global_load_lds_dwordx4 v[226:227], off
	s_waitcnt vmcnt(6)
	s_waitcnt lgkmcnt(0)
	s_barrier
; #define PG8_STAGE(bufoff, gbase, voff) do { _Pragma("unroll") for (int _i = 0; _i < 2; ++_i) \
;         __builtin_amdgcn_global_load_lds((const unsigned*)((const char*)(gbase) + (voff)[_i]), (PG8_LAS unsigned*)(lds + (bufoff) + ldsw + _i * 8192), 16, 0, 0); } while (0)
; #define PG8_LDA(dst, b, h) do { _Pragma("unroll") for (int m = 0; m < 4; ++m) _Pragma("unroll") for (int k = 0; k < 2; ++k) dst[m][k] = *(const PG8_LAS bf16x8*)(lds + PG8_SA(b, h) + aoff + m * 2048 + k * 1024); } while (0)
; #define PG8_LDB(dst, b, h) do { _Pragma("unroll") for (int n = 0; n < 2; ++n) _Pragma("unroll") for (int k = 0; k < 2; ++k) dst[n][k] = *(const PG8_LAS bf16x8*)(lds + PG8_SB(b, h) + boff + n * 2048 + k * 1024); } while (0)
; #define PG8_MMA(ai, bj, At, Bt) do { __builtin_amdgcn_s_setprio(1); _Pragma("unroll") for (int m = 0; m < 4; ++m) _Pragma("unroll") for (int n = 0; n < 2; ++n) _Pragma("unroll") for (int k = 0; k < 2; ++k) \
;         acc[ai][bj][m][n] = __builtin_amdgcn_mfma_f32_16x16x32_bf16(Bt[n][k], At[m][k], acc[ai][bj][m][n], 0, 0, 0); __builtin_amdgcn_s_setprio(0); } while (0)
; #define PG8_WAIT_V(n) asm volatile("s_waitcnt vmcnt(" #n ")" ::: "memory")
; template <class Epi, class Sched, bool ALIGN_EPI = false, bool SP2 = false>
; __device__ __forceinline__ void gemm_phase(PG8_LAS unsigned char* lds, const Gemm g, const Sched& S, const Epi& E) {
;     ...
;             PG8_LDB(B0, 0, 0); PG8_LDB(B1, 0, 1); PG8_SCHED; PG8_LDA(At, 0, 0); PG8_STAGE(PG8_SA(1, 1), a1 + hstep, voffA);
;             PG8_WAIT_V(8); PG8_WAIT_L(0); PG8_BAR; PG8_MMA(0, 0, At, B0); PG8_MMA(0, 1, At, B1); PG8_BAR; PG8_SCHED;
;             PG8_LDA(At, 0, 1); PG8_STAGE(PG8_SB(0, 0), b2, voffB); PG8_STAGE(PG8_SB(0, 1), b2 + hstep, voffB); PG8_STAGE(PG8_SA(0, 0), a2, voffA);
;             PG8_WAIT_V(8); PG8_WAIT_L(0); PG8_BAR; PG8_MMA(1, 0, At, B0); PG8_MMA(1, 1, At, B1); PG8_BAR; PG8_SCHED;
;             PG8_LDB(B0, 1, 0); PG8_LDB(B1, 1, 1); PG8_SCHED; PG8_LDA(At, 1, 0); PG8_STAGE(PG8_SA(0, 1), a2 + hstep, voffA);
;             PG8_WAIT_V(8); PG8_WAIT_L(0); PG8_BAR; PG8_MMA(0, 0, At, B0); PG8_MMA(0, 1, At, B1); PG8_BAR; PG8_SCHED;
;             PG8_LDA(At, 1, 1); PG8_STAGE(PG8_SB(1, 0), b3, voffB); PG8_STAGE(PG8_SB(1, 1), b3 + hstep, voffB); PG8_STAGE(PG8_SA(1, 0), a3, voffA);
;             PG8_WAIT_V(8); PG8_WAIT_L(0); PG8_BAR; PG8_MMA(1, 0, At, B0); PG8_MMA(1, 1, At, B1); PG8_BAR; PG8_SCHED;
	s_setprio 1
	s_waitcnt lgkmcnt(0)
	v_mfma_f32_16x16x32_bf16 v[60:63], v[128:131], v[190:193], v[60:63]
	v_mfma_f32_16x16x32_bf16 v[56:59], v[160:163], v[190:193], v[56:59]
	v_mfma_f32_16x16x32_bf16 v[44:47], v[128:131], v[198:201], v[44:47]
	v_mfma_f32_16x16x32_bf16 v[40:43], v[160:163], v[198:201], v[40:43]
	v_mfma_f32_16x16x32_bf16 v[28:31], v[128:131], v[206:209], v[28:31]
	v_mfma_f32_16x16x32_bf16 v[24:27], v[160:163], v[206:209], v[24:27]
	v_mfma_f32_16x16x32_bf16 v[12:15], v[128:131], v[214:217], v[12:15]
	v_mfma_f32_16x16x32_bf16 v[8:11], v[160:163], v[214:217], v[8:11]
	v_mfma_f32_16x16x32_bf16 v[60:63], v[156:159], v[194:197], v[60:63]
	v_mfma_f32_16x16x32_bf16 v[56:59], v[170:173], v[194:197], v[56:59]
	v_mfma_f32_16x16x32_bf16 v[44:47], v[156:159], v[202:205], v[44:47]
	v_mfma_f32_16x16x32_bf16 v[40:43], v[170:173], v[202:205], v[40:43]
	v_mfma_f32_16x16x32_bf16 v[28:31], v[156:159], v[210:213], v[28:31]
	v_mfma_f32_16x16x32_bf16 v[24:27], v[170:173], v[210:213], v[24:27]
	v_mfma_f32_16x16x32_bf16 v[12:15], v[156:159], v[218:221], v[12:15]
	v_mfma_f32_16x16x32_bf16 v[8:11], v[170:173], v[218:221], v[8:11]
	s_setprio 0
	s_setprio 1
	v_mfma_f32_16x16x32_bf16 v[52:55], v[174:177], v[190:193], v[52:55]
	v_mfma_f32_16x16x32_bf16 v[48:51], v[182:185], v[190:193], v[48:51]
	v_mfma_f32_16x16x32_bf16 v[36:39], v[174:177], v[198:201], v[36:39]
	v_mfma_f32_16x16x32_bf16 v[32:35], v[182:185], v[198:201], v[32:35]
	v_mfma_f32_16x16x32_bf16 v[20:23], v[174:177], v[206:209], v[20:23]
	v_mfma_f32_16x16x32_bf16 v[16:19], v[182:185], v[206:209], v[16:19]
	v_mfma_f32_16x16x32_bf16 v[4:7], v[174:177], v[214:217], v[4:7]
	v_mfma_f32_16x16x32_bf16 v[0:3], v[182:185], v[214:217], v[0:3]
	v_mfma_f32_16x16x32_bf16 v[52:55], v[178:181], v[194:197], v[52:55]
	v_mfma_f32_16x16x32_bf16 v[48:51], v[186:189], v[194:197], v[48:51]
	v_mfma_f32_16x16x32_bf16 v[36:39], v[178:181], v[202:205], v[36:39]
	v_mfma_f32_16x16x32_bf16 v[32:35], v[186:189], v[202:205], v[32:35]
	v_mfma_f32_16x16x32_bf16 v[20:23], v[178:181], v[210:213], v[20:23]
	v_mfma_f32_16x16x32_bf16 v[16:19], v[186:189], v[210:213], v[16:19]
	v_mfma_f32_16x16x32_bf16 v[4:7], v[178:181], v[218:221], v[4:7]
	v_mfma_f32_16x16x32_bf16 v[0:3], v[186:189], v[218:221], v[0:3]
	s_setprio 0
	s_barrier
	s_add_i32 s82, 0, 0x18000
	v_add_u32_e32 v140, s82, v164
	s_add_i32 s83, 0, 0x1c000
	ds_read_b128 v[128:131], v140
	ds_read_b128 v[156:159], v140 offset:1024
	ds_read_b128 v[160:163], v140 offset:2048
	ds_read_b128 v[170:173], v140 offset:3072
	v_add_u32_e32 v140, s83, v164
	ds_read_b128 v[174:177], v140
	ds_read_b128 v[178:181], v140 offset:1024
	ds_read_b128 v[182:185], v140 offset:2048
	ds_read_b128 v[186:189], v140 offset:3072
	v_lshl_add_u64 v[226:227], s[52:53], 0, v[132:133]
	s_add_u32 s52, s52, 0x80000
	s_addc_u32 s53, s53, 0
	s_mov_b32 m0, s47
	v_lshl_add_u64 v[230:231], s[52:53], 0, v[132:133]
	ds_read_b128 v[190:193], v167 offset:32768
	ds_read_b128 v[194:197], v167 offset:33792
	ds_read_b128 v[198:201], v167 offset:34816
	ds_read_b128 v[202:205], v167 offset:35840
	ds_read_b128 v[206:209], v167 offset:36864
	ds_read_b128 v[210:213], v167 offset:37888
	ds_read_b128 v[214:217], v167 offset:38912
	ds_read_b128 v[218:221], v167 offset:39936
	global_load_lds_dwordx4 v[226:227], off
	s_mov_b32 m0, s57
	s_nop 0
	global_load_lds_dwordx4 v[228:229], off
	s_mov_b32 m0, s58
	s_nop 0
	global_load_lds_dwordx4 v[230:231], off
	v_lshl_add_u64 v[230:231], s[52:53], 0, v[136:137]
	s_mov_b32 m0, s59
	s_nop 0
	global_load_lds_dwordx4 v[230:231], off
	s_waitcnt vmcnt(8)
	s_waitcnt lgkmcnt(0)
	s_barrier
	s_setprio 1
	s_waitcnt lgkmcnt(0)
	v_mfma_f32_16x16x32_bf16 v[124:127], v[128:131], v[190:193], v[124:127]
	v_mfma_f32_16x16x32_bf16 v[120:123], v[160:163], v[190:193], v[120:123]
	v_mfma_f32_16x16x32_bf16 v[108:111], v[128:131], v[198:201], v[108:111]
	v_mfma_f32_16x16x32_bf16 v[104:107], v[160:163], v[198:201], v[104:107]
	v_mfma_f32_16x16x32_bf16 v[92:95], v[128:131], v[206:209], v[92:95]
	v_mfma_f32_16x16x32_bf16 v[88:91], v[160:163], v[206:209], v[88:91]
	v_mfma_f32_16x16x32_bf16 v[76:79], v[128:131], v[214:217], v[76:79]
	v_mfma_f32_16x16x32_bf16 v[72:75], v[160:163], v[214:217], v[72:75]
	v_mfma_f32_16x16x32_bf16 v[124:127], v[156:159], v[194:197], v[124:127]
	v_mfma_f32_16x16x32_bf16 v[120:123], v[170:173], v[194:197], v[120:123]
	v_mfma_f32_16x16x32_bf16 v[108:111], v[156:159], v[202:205], v[108:111]
	v_mfma_f32_16x16x32_bf16 v[104:107], v[170:173], v[202:205], v[104:107]
	v_mfma_f32_16x16x32_bf16 v[92:95], v[156:159], v[210:213], v[92:95]
	v_mfma_f32_16x16x32_bf16 v[88:91], v[170:173], v[210:213], v[88:91]
	v_mfma_f32_16x16x32_bf16 v[76:79], v[156:159], v[218:221], v[76:79]
	v_mfma_f32_16x16x32_bf16 v[72:75], v[170:173], v[218:221], v[72:75]
	s_setprio 0
	s_setprio 1
	v_mfma_f32_16x16x32_bf16 v[116:119], v[174:177], v[190:193], v[116:119]
	v_mfma_f32_16x16x32_bf16 v[112:115], v[182:185], v[190:193], v[112:115]
	v_mfma_f32_16x16x32_bf16 v[100:103], v[174:177], v[198:201], v[100:103]
	v_mfma_f32_16x16x32_bf16 v[96:99], v[182:185], v[198:201], v[96:99]
	v_mfma_f32_16x16x32_bf16 v[84:87], v[174:177], v[206:209], v[84:87]
	v_mfma_f32_16x16x32_bf16 v[80:83], v[182:185], v[206:209], v[80:83]
	v_mfma_f32_16x16x32_bf16 v[68:71], v[174:177], v[214:217], v[68:71]
	v_mfma_f32_16x16x32_bf16 v[64:67], v[182:185], v[214:217], v[64:67]
	v_mfma_f32_16x16x32_bf16 v[116:119], v[178:181], v[194:197], v[116:119]
	v_mfma_f32_16x16x32_bf16 v[112:115], v[186:189], v[194:197], v[112:115]
	v_mfma_f32_16x16x32_bf16 v[100:103], v[178:181], v[202:205], v[100:103]
	v_mfma_f32_16x16x32_bf16 v[96:99], v[186:189], v[202:205], v[96:99]
	v_mfma_f32_16x16x32_bf16 v[84:87], v[178:181], v[210:213], v[84:87]
	v_mfma_f32_16x16x32_bf16 v[80:83], v[186:189], v[210:213], v[80:83]
	v_mfma_f32_16x16x32_bf16 v[68:71], v[178:181], v[218:221], v[68:71]
	v_mfma_f32_16x16x32_bf16 v[64:67], v[186:189], v[218:221], v[64:67]
	s_setprio 0
	s_barrier
; #define PG8_STAGE(bufoff, gbase, voff) do { _Pragma("unroll") for (int _i = 0; _i < 2; ++_i) \
;         __builtin_amdgcn_global_load_lds((const unsigned*)((const char*)(gbase) + (voff)[_i]), (PG8_LAS unsigned*)(lds + (bufoff) + ldsw + _i * 8192), 16, 0, 0); } while (0)
; #define PG8_LDA(dst, b, h) do { _Pragma("unroll") for (int m = 0; m < 4; ++m) _Pragma("unroll") for (int k = 0; k < 2; ++k) dst[m][k] = *(const PG8_LAS bf16x8*)(lds + PG8_SA(b, h) + aoff + m * 2048 + k * 1024); } while (0)
; #define PG8_LDB(dst, b, h) do { _Pragma("unroll") for (int n = 0; n < 2; ++n) _Pragma("unroll") for (int k = 0; k < 2; ++k) dst[n][k] = *(const PG8_LAS bf16x8*)(lds + PG8_SB(b, h) + boff + n * 2048 + k * 1024); } while (0)
; #define PG8_MMA(ai, bj, At, Bt) do { __builtin_amdgcn_s_setprio(1); _Pragma("unroll") for (int m = 0; m < 4; ++m) _Pragma("unroll") for (int n = 0; n < 2; ++n) _Pragma("unroll") for (int k = 0; k < 2; ++k) \
;         acc[ai][bj][m][n] = __builtin_amdgcn_mfma_f32_16x16x32_bf16(Bt[n][k], At[m][k], acc[ai][bj][m][n], 0, 0, 0); __builtin_amdgcn_s_setprio(0); } while (0)
; #define PG8_WAIT_V(n) asm volatile("s_waitcnt vmcnt(" #n ")" ::: "memory")
; template <class Epi, class Sched, bool ALIGN_EPI = false, bool SP2 = false>
; __device__ __forceinline__ void gemm_phase(PG8_LAS unsigned char* lds, const Gemm g, const Sched& S, const Epi& E) {
;     ...
;             PG8_LDB(B0, 0, 0); PG8_LDB(B1, 0, 1); PG8_SCHED; PG8_LDA(At, 0, 0); PG8_STAGE(PG8_SA(1, 1), a1 + hstep, voffA);
;             PG8_WAIT_V(8); PG8_WAIT_L(0); PG8_BAR; PG8_MMA(0, 0, At, B0); PG8_MMA(0, 1, At, B1); PG8_BAR; PG8_SCHED;
;             PG8_LDA(At, 0, 1); PG8_STAGE(PG8_SB(0, 0), b2, voffB); PG8_STAGE(PG8_SB(0, 1), b2 + hstep, voffB); PG8_STAGE(PG8_SA(0, 0), a2, voffA);
;             PG8_WAIT_V(8); PG8_WAIT_L(0); PG8_BAR; PG8_MMA(1, 0, At, B0); PG8_MMA(1, 1, At, B1); PG8_BAR; PG8_SCHED;
;             PG8_LDB(B0, 1, 0); PG8_LDB(B1, 1, 1); PG8_SCHED; PG8_LDA(At, 1, 0); PG8_STAGE(PG8_SA(0, 1), a2 + hstep, voffA);
;             PG8_WAIT_V(8); PG8_WAIT_L(0); PG8_BAR; PG8_MMA(0, 0, At, B0); PG8_MMA(0, 1, At, B1); PG8_BAR; PG8_SCHED;
;             PG8_LDA(At, 1, 1); PG8_STAGE(PG8_SB(1, 0), b3, voffB); PG8_STAGE(PG8_SB(1, 1), b3 + hstep, voffB); PG8_STAGE(PG8_SA(1, 0), a3, voffA);
;             PG8_WAIT_V(8); PG8_WAIT_L(0); PG8_BAR; PG8_MMA(1, 0, At, B0); PG8_MMA(1, 1, At, B1); PG8_BAR; PG8_SCHED;
	s_add_i32 s52, s82, s56
	v_lshl_add_u64 v[222:223], v[222:223], 0, s[10:11]
	s_mov_b32 m0, s52
	ds_read_b128 v[190:193], v167 offset:49152
	ds_read_b128 v[194:197], v167 offset:50176
	ds_read_b128 v[198:201], v167 offset:51200
	ds_read_b128 v[202:205], v167 offset:52224
	ds_read_b128 v[206:209], v167 offset:53248
	ds_read_b128 v[210:213], v167 offset:54272
	ds_read_b128 v[214:217], v167 offset:55296
	ds_read_b128 v[218:221], v167 offset:56320
	global_load_lds_dwordx4 v[222:223], off
	s_add_i32 m0, s52, 0x2000
	s_add_u32 s50, s50, 0x80080
	v_lshl_add_u64 v[222:223], v[224:225], 0, s[10:11]
	s_addc_u32 s51, s51, 0
	s_add_i32 s52, s83, s56
	global_load_lds_dwordx4 v[222:223], off
	v_lshl_add_u64 v[222:223], s[50:51], 0, v[134:135]
	s_mov_b32 m0, s52
	s_nop 0
	global_load_lds_dwordx4 v[222:223], off
	v_lshl_add_u64 v[222:223], s[50:51], 0, v[138:139]
	s_add_i32 m0, s52, 0x2000
	s_nop 0
	global_load_lds_dwordx4 v[222:223], off
	s_waitcnt vmcnt(6)
	s_waitcnt lgkmcnt(0)
	s_barrier
	s_setprio 1
	s_waitcnt lgkmcnt(0)
	v_mfma_f32_16x16x32_bf16 v[60:63], v[128:131], v[190:193], v[60:63]
	v_mfma_f32_16x16x32_bf16 v[56:59], v[160:163], v[190:193], v[56:59]
	v_mfma_f32_16x16x32_bf16 v[44:47], v[128:131], v[198:201], v[44:47]
	v_mfma_f32_16x16x32_bf16 v[40:43], v[160:163], v[198:201], v[40:43]
	v_mfma_f32_16x16x32_bf16 v[28:31], v[128:131], v[206:209], v[28:31]
	v_mfma_f32_16x16x32_bf16 v[24:27], v[160:163], v[206:209], v[24:27]
	v_mfma_f32_16x16x32_bf16 v[12:15], v[128:131], v[214:217], v[12:15]
	v_mfma_f32_16x16x32_bf16 v[8:11], v[160:163], v[214:217], v[8:11]
	v_mfma_f32_16x16x32_bf16 v[60:63], v[156:159], v[194:197], v[60:63]
	v_mfma_f32_16x16x32_bf16 v[56:59], v[170:173], v[194:197], v[56:59]
	v_mfma_f32_16x16x32_bf16 v[44:47], v[156:159], v[202:205], v[44:47]
	v_mfma_f32_16x16x32_bf16 v[40:43], v[170:173], v[202:205], v[40:43]
	v_mfma_f32_16x16x32_bf16 v[28:31], v[156:159], v[210:213], v[28:31]
	v_mfma_f32_16x16x32_bf16 v[24:27], v[170:173], v[210:213], v[24:27]
	v_mfma_f32_16x16x32_bf16 v[12:15], v[156:159], v[218:221], v[12:15]
	v_mfma_f32_16x16x32_bf16 v[8:11], v[170:173], v[218:221], v[8:11]
	s_setprio 0
	s_setprio 1
	v_mfma_f32_16x16x32_bf16 v[52:55], v[174:177], v[190:193], v[52:55]
	v_mfma_f32_16x16x32_bf16 v[48:51], v[182:185], v[190:193], v[48:51]
	v_mfma_f32_16x16x32_bf16 v[36:39], v[174:177], v[198:201], v[36:39]
	v_mfma_f32_16x16x32_bf16 v[32:35], v[182:185], v[198:201], v[32:35]
	v_mfma_f32_16x16x32_bf16 v[20:23], v[174:177], v[206:209], v[20:23]
	v_mfma_f32_16x16x32_bf16 v[16:19], v[182:185], v[206:209], v[16:19]
	v_mfma_f32_16x16x32_bf16 v[4:7], v[174:177], v[214:217], v[4:7]
	v_mfma_f32_16x16x32_bf16 v[0:3], v[182:185], v[214:217], v[0:3]
	v_mfma_f32_16x16x32_bf16 v[52:55], v[178:181], v[194:197], v[52:55]
	v_mfma_f32_16x16x32_bf16 v[48:51], v[186:189], v[194:197], v[48:51]
	v_mfma_f32_16x16x32_bf16 v[36:39], v[178:181], v[202:205], v[36:39]
	v_mfma_f32_16x16x32_bf16 v[32:35], v[186:189], v[202:205], v[32:35]
	v_mfma_f32_16x16x32_bf16 v[20:23], v[178:181], v[210:213], v[20:23]
	v_mfma_f32_16x16x32_bf16 v[16:19], v[186:189], v[210:213], v[16:19]
	v_mfma_f32_16x16x32_bf16 v[4:7], v[178:181], v[218:221], v[4:7]
	v_mfma_f32_16x16x32_bf16 v[0:3], v[186:189], v[218:221], v[0:3]
	s_setprio 0
	s_barrier
	s_add_i32 s81, s81, 2
	s_add_u32 s48, s48, 0x100
	s_addc_u32 s49, s49, 0
	s_add_u32 s76, s76, 0x100
	s_addc_u32 s77, s77, 0
	s_cmp_gt_u32 s81, 29
	s_cbranch_scc0 .LBB0_766
	s_and_b64 vcc, exec, s[12:13]
	s_cbranch_vccnz .LBB0_771
	v_lshl_add_u32 v156, s36, 8, v143
	s_cmp_gt_i32 s46, 3
	s_mov_b64 s[36:37], -1
	s_cbranch_scc1 .LBB0_772

; #define PG8_STAGE(bufoff, gbase, voff) do { _Pragma("unroll") for (int _i = 0; _i < 2; ++_i) \
;         __builtin_amdgcn_global_load_lds((const unsigned*)((const char*)(gbase) + (voff)[_i]), (PG8_LAS unsigned*)(lds + (bufoff) + ldsw + _i * 8192), 16, 0, 0); } while (0)
; #define PG8_LDA(dst, b, h) do { _Pragma("unroll") for (int m = 0; m < 4; ++m) _Pragma("unroll") for (int k = 0; k < 2; ++k) dst[m][k] = *(const PG8_LAS bf16x8*)(lds + PG8_SA(b, h) + aoff + m * 2048 + k * 1024); } while (0)
; #define PG8_LDB(dst, b, h) do { _Pragma("unroll") for (int n = 0; n < 2; ++n) _Pragma("unroll") for (int k = 0; k < 2; ++k) dst[n][k] = *(const PG8_LAS bf16x8*)(lds + PG8_SB(b, h) + boff + n * 2048 + k * 1024); } while (0)
; #define PG8_MMA(ai, bj, At, Bt) do { __builtin_amdgcn_s_setprio(1); _Pragma("unroll") for (int m = 0; m < 4; ++m) _Pragma("unroll") for (int n = 0; n < 2; ++n) _Pragma("unroll") for (int k = 0; k < 2; ++k) \
;         acc[ai][bj][m][n] = __builtin_amdgcn_mfma_f32_16x16x32_bf16(Bt[n][k], At[m][k], acc[ai][bj][m][n], 0, 0, 0); __builtin_amdgcn_s_setprio(0); } while (0)
; #define PG8_WAIT_V(n) asm volatile("s_waitcnt vmcnt(" #n ")" ::: "memory")
; #define PG8_WAIT_L(n) asm volatile("s_waitcnt lgkmcnt(" #n ")" ::: "memory")
; #define PG8_BAR __builtin_amdgcn_s_barrier()
; #define PG8_SCHED __builtin_amdgcn_sched_barrier(0)
; template <class Epi, class Sched, bool ALIGN_EPI = false, bool SP2 = false>
; __device__ __forceinline__ void gemm_phase(PG8_LAS unsigned char* lds, const Gemm g, const Sched& S, const Epi& E) {
;     ...
;             PG8_LDB(B0, 0, 0); PG8_LDB(B1, 0, 1); PG8_SCHED; PG8_LDA(At, 0, 0); PG8_STAGE(PG8_SA(1, 1), a1 + hstep, voffA);
;             PG8_WAIT_V(8); PG8_WAIT_L(0); PG8_BAR; PG8_MMA(0, 0, At, B0); PG8_MMA(0, 1, At, B1); PG8_BAR; PG8_SCHED;
;             PG8_LDA(At, 0, 1); PG8_STAGE(PG8_SB(0, 0), b2, voffB); PG8_STAGE(PG8_SB(0, 1), b2 + hstep, voffB); PG8_STAGE(PG8_SA(0, 0), a2, voffA);
;             PG8_WAIT_V(8); PG8_WAIT_L(0); PG8_BAR; PG8_MMA(1, 0, At, B0); PG8_MMA(1, 1, At, B1); PG8_BAR; PG8_SCHED;
.LBB0_1073:
	ds_read_b128 v[116:119], v165
	ds_read_b128 v[124:127], v165 offset:1024
	ds_read_b128 v[128:131], v165 offset:2048
	ds_read_b128 v[132:135], v165 offset:3072
	ds_read_b128 v[156:159], v166
	ds_read_b128 v[170:173], v166 offset:1024
	ds_read_b128 v[174:177], v166 offset:2048
	ds_read_b128 v[178:181], v166 offset:3072
	s_add_u32 s60, s30, 0xfff80000
	s_addc_u32 s61, s31, -1
	s_add_u32 s34, s30, 0xfff80080
	s_addc_u32 s35, s31, -1
	s_cmp_eq_u32 s58, 28
	s_cselect_b32 s37, s23, s35
	s_cselect_b32 s36, s54, s34
	s_cselect_b32 s35, s21, s57
	s_cselect_b32 s34, s55, s56
	v_lshl_add_u64 v[160:161], s[60:61], 0, v[148:149]
	s_mov_b32 m0, s47
	ds_read_b128 v[182:185], v167
	ds_read_b128 v[186:189], v167 offset:1024
	ds_read_b128 v[190:193], v167 offset:2048
	ds_read_b128 v[194:197], v167 offset:3072
	ds_read_b128 v[198:201], v167 offset:4096
	ds_read_b128 v[202:205], v167 offset:5120
	ds_read_b128 v[206:209], v167 offset:6144
	ds_read_b128 v[210:213], v167 offset:7168
	global_load_lds_dwordx4 v[160:161], off
	v_lshl_add_u64 v[160:161], s[60:61], 0, v[150:151]
	s_mov_b32 m0, s48
	s_nop 0
	global_load_lds_dwordx4 v[160:161], off
	v_lshl_add_u64 v[160:161], s[30:31], 0, v[148:149]
	s_add_i32 m0, s29, 0xc000
	s_nop 0
	global_load_lds_dwordx4 v[160:161], off
	v_lshl_add_u64 v[160:161], s[30:31], 0, v[150:151]
	s_add_i32 m0, s29, 0xe000
	s_nop 0
	global_load_lds_dwordx4 v[160:161], off
	s_waitcnt vmcnt(8)
	s_waitcnt lgkmcnt(0)
	s_barrier
	s_setprio 1
	s_waitcnt lgkmcnt(0)
	v_mfma_f32_16x16x32_bf16 v[140:143], v[116:119], v[182:185], v[140:143]
	v_mfma_f32_16x16x32_bf16 v[136:139], v[128:131], v[182:185], v[136:139]
	v_mfma_f32_16x16x32_bf16 v[108:111], v[116:119], v[190:193], v[108:111]
	v_mfma_f32_16x16x32_bf16 v[104:107], v[128:131], v[190:193], v[104:107]
	v_mfma_f32_16x16x32_bf16 v[92:95], v[116:119], v[198:201], v[92:95]
	v_mfma_f32_16x16x32_bf16 v[88:91], v[128:131], v[198:201], v[88:91]
	v_mfma_f32_16x16x32_bf16 v[76:79], v[116:119], v[206:209], v[76:79]
	v_mfma_f32_16x16x32_bf16 v[72:75], v[128:131], v[206:209], v[72:75]
	v_mfma_f32_16x16x32_bf16 v[140:143], v[124:127], v[186:189], v[140:143]
	v_mfma_f32_16x16x32_bf16 v[136:139], v[132:135], v[186:189], v[136:139]
	v_mfma_f32_16x16x32_bf16 v[108:111], v[124:127], v[194:197], v[108:111]
	v_mfma_f32_16x16x32_bf16 v[104:107], v[132:135], v[194:197], v[104:107]
	v_mfma_f32_16x16x32_bf16 v[92:95], v[124:127], v[202:205], v[92:95]
	v_mfma_f32_16x16x32_bf16 v[88:91], v[132:135], v[202:205], v[88:91]
	v_mfma_f32_16x16x32_bf16 v[76:79], v[124:127], v[210:213], v[76:79]
	v_mfma_f32_16x16x32_bf16 v[72:75], v[132:135], v[210:213], v[72:75]
	s_setprio 0
	s_setprio 1
	v_mfma_f32_16x16x32_bf16 v[120:123], v[156:159], v[182:185], v[120:123]
	v_mfma_f32_16x16x32_bf16 v[112:115], v[174:177], v[182:185], v[112:115]
	v_mfma_f32_16x16x32_bf16 v[100:103], v[156:159], v[190:193], v[100:103]
	v_mfma_f32_16x16x32_bf16 v[96:99], v[174:177], v[190:193], v[96:99]
	v_mfma_f32_16x16x32_bf16 v[84:87], v[156:159], v[198:201], v[84:87]
	v_mfma_f32_16x16x32_bf16 v[80:83], v[174:177], v[198:201], v[80:83]
	v_mfma_f32_16x16x32_bf16 v[68:71], v[156:159], v[206:209], v[68:71]
	v_mfma_f32_16x16x32_bf16 v[64:67], v[174:177], v[206:209], v[64:67]
	v_mfma_f32_16x16x32_bf16 v[120:123], v[170:173], v[186:189], v[120:123]
	v_mfma_f32_16x16x32_bf16 v[112:115], v[178:181], v[186:189], v[112:115]
	v_mfma_f32_16x16x32_bf16 v[100:103], v[170:173], v[194:197], v[100:103]
	v_mfma_f32_16x16x32_bf16 v[96:99], v[178:181], v[194:197], v[96:99]
	v_mfma_f32_16x16x32_bf16 v[84:87], v[170:173], v[202:205], v[84:87]
	v_mfma_f32_16x16x32_bf16 v[80:83], v[178:181], v[202:205], v[80:83]
	v_mfma_f32_16x16x32_bf16 v[68:71], v[170:173], v[210:213], v[68:71]
	v_mfma_f32_16x16x32_bf16 v[64:67], v[178:181], v[210:213], v[64:67]
	s_setprio 0
	s_barrier
	s_add_i32 s59, s51, s40
	v_lshl_add_u64 v[160:161], s[34:35], 0, v[144:145]
	s_mov_b32 m0, s59
	ds_read_b128 v[182:185], v167 offset:16384
	ds_read_b128 v[186:189], v167 offset:17408
	ds_read_b128 v[190:193], v167 offset:18432
	ds_read_b128 v[194:197], v167 offset:19456
	ds_read_b128 v[198:201], v167 offset:20480
	ds_read_b128 v[202:205], v167 offset:21504
	ds_read_b128 v[206:209], v167 offset:22528
	ds_read_b128 v[210:213], v167 offset:23552
	global_load_lds_dwordx4 v[160:161], off
	s_add_i32 m0, s59, 0x2000
	s_add_u32 s60, s34, 0x80000
	v_lshl_add_u64 v[214:215], s[34:35], 0, v[146:147]
	s_addc_u32 s61, s35, 0
	s_add_i32 s59, s52, s40
	global_load_lds_dwordx4 v[214:215], off
	v_lshl_add_u64 v[216:217], s[60:61], 0, v[144:145]
	s_mov_b32 m0, s59
	v_lshl_add_u64 v[218:219], s[36:37], 0, v[146:147]
	global_load_lds_dwordx4 v[216:217], off
	v_lshl_add_u64 v[216:217], s[60:61], 0, v[146:147]
	s_add_i32 m0, s59, 0x2000
	s_nop 0
	global_load_lds_dwordx4 v[216:217], off
	s_waitcnt vmcnt(6)
	s_waitcnt lgkmcnt(0)
	s_barrier
; #define PG8_STAGE(bufoff, gbase, voff) do { _Pragma("unroll") for (int _i = 0; _i < 2; ++_i) \
;         __builtin_amdgcn_global_load_lds((const unsigned*)((const char*)(gbase) + (voff)[_i]), (PG8_LAS unsigned*)(lds + (bufoff) + ldsw + _i * 8192), 16, 0, 0); } while (0)
; #define PG8_LDA(dst, b, h) do { _Pragma("unroll") for (int m = 0; m < 4; ++m) _Pragma("unroll") for (int k = 0; k < 2; ++k) dst[m][k] = *(const PG8_LAS bf16x8*)(lds + PG8_SA(b, h) + aoff + m * 2048 + k * 1024); } while (0)
; #define PG8_LDB(dst, b, h) do { _Pragma("unroll") for (int n = 0; n < 2; ++n) _Pragma("unroll") for (int k = 0; k < 2; ++k) dst[n][k] = *(const PG8_LAS bf16x8*)(lds + PG8_SB(b, h) + boff + n * 2048 + k * 1024); } while (0)
; #define PG8_MMA(ai, bj, At, Bt) do { __builtin_amdgcn_s_setprio(1); _Pragma("unroll") for (int m = 0; m < 4; ++m) _Pragma("unroll") for (int n = 0; n < 2; ++n) _Pragma("unroll") for (int k = 0; k < 2; ++k) \
;         acc[ai][bj][m][n] = __builtin_amdgcn_mfma_f32_16x16x32_bf16(Bt[n][k], At[m][k], acc[ai][bj][m][n], 0, 0, 0); __builtin_amdgcn_s_setprio(0); } while (0)
; #define PG8_WAIT_V(n) asm volatile("s_waitcnt vmcnt(" #n ")" ::: "memory")
; #define PG8_WAIT_L(n) asm volatile("s_waitcnt lgkmcnt(" #n ")" ::: "memory")
; #define PG8_BAR __builtin_amdgcn_s_barrier()
; #define PG8_SCHED __builtin_amdgcn_sched_barrier(0)
; template <class Epi, class Sched, bool ALIGN_EPI = false, bool SP2 = false>
; __device__ __forceinline__ void gemm_phase(PG8_LAS unsigned char* lds, const Gemm g, const Sched& S, const Epi& E) {
;     ...
;             PG8_WAIT_V(8); PG8_WAIT_L(0); PG8_BAR; PG8_MMA(1, 0, At, B0); PG8_MMA(1, 1, At, B1); PG8_BAR; PG8_SCHED;
;             PG8_LDB(B0, 1, 0); PG8_LDB(B1, 1, 1); PG8_SCHED; PG8_LDA(At, 1, 0); PG8_STAGE(PG8_SA(0, 1), a2 + hstep, voffA);
;             PG8_WAIT_V(8); PG8_WAIT_L(0); PG8_BAR; PG8_MMA(0, 0, At, B0); PG8_MMA(0, 1, At, B1); PG8_BAR; PG8_SCHED;
	s_setprio 1
	s_waitcnt lgkmcnt(0)
	v_mfma_f32_16x16x32_bf16 v[60:63], v[116:119], v[182:185], v[60:63]
	v_mfma_f32_16x16x32_bf16 v[56:59], v[128:131], v[182:185], v[56:59]
	v_mfma_f32_16x16x32_bf16 v[44:47], v[116:119], v[190:193], v[44:47]
	v_mfma_f32_16x16x32_bf16 v[40:43], v[128:131], v[190:193], v[40:43]
	v_mfma_f32_16x16x32_bf16 v[28:31], v[116:119], v[198:201], v[28:31]
	v_mfma_f32_16x16x32_bf16 v[24:27], v[128:131], v[198:201], v[24:27]
	v_mfma_f32_16x16x32_bf16 v[12:15], v[116:119], v[206:209], v[12:15]
	v_mfma_f32_16x16x32_bf16 v[8:11], v[128:131], v[206:209], v[8:11]
	v_mfma_f32_16x16x32_bf16 v[60:63], v[124:127], v[186:189], v[60:63]
	v_mfma_f32_16x16x32_bf16 v[56:59], v[132:135], v[186:189], v[56:59]
	v_mfma_f32_16x16x32_bf16 v[44:47], v[124:127], v[194:197], v[44:47]
	v_mfma_f32_16x16x32_bf16 v[40:43], v[132:135], v[194:197], v[40:43]
	v_mfma_f32_16x16x32_bf16 v[28:31], v[124:127], v[202:205], v[28:31]
	v_mfma_f32_16x16x32_bf16 v[24:27], v[132:135], v[202:205], v[24:27]
	v_mfma_f32_16x16x32_bf16 v[12:15], v[124:127], v[210:213], v[12:15]
	v_mfma_f32_16x16x32_bf16 v[8:11], v[132:135], v[210:213], v[8:11]
	s_setprio 0
	s_setprio 1
	v_mfma_f32_16x16x32_bf16 v[52:55], v[156:159], v[182:185], v[52:55]
	v_mfma_f32_16x16x32_bf16 v[48:51], v[174:177], v[182:185], v[48:51]
	v_mfma_f32_16x16x32_bf16 v[36:39], v[156:159], v[190:193], v[36:39]
	v_mfma_f32_16x16x32_bf16 v[32:35], v[174:177], v[190:193], v[32:35]
	v_mfma_f32_16x16x32_bf16 v[20:23], v[156:159], v[198:201], v[20:23]
	v_mfma_f32_16x16x32_bf16 v[16:19], v[174:177], v[198:201], v[16:19]
	v_mfma_f32_16x16x32_bf16 v[4:7], v[156:159], v[206:209], v[4:7]
	v_mfma_f32_16x16x32_bf16 v[0:3], v[174:177], v[206:209], v[0:3]
	v_mfma_f32_16x16x32_bf16 v[52:55], v[170:173], v[186:189], v[52:55]
	v_mfma_f32_16x16x32_bf16 v[48:51], v[178:181], v[186:189], v[48:51]
	v_mfma_f32_16x16x32_bf16 v[36:39], v[170:173], v[194:197], v[36:39]
	v_mfma_f32_16x16x32_bf16 v[32:35], v[178:181], v[194:197], v[32:35]
	v_mfma_f32_16x16x32_bf16 v[20:23], v[170:173], v[202:205], v[20:23]
	v_mfma_f32_16x16x32_bf16 v[16:19], v[178:181], v[202:205], v[16:19]
	v_mfma_f32_16x16x32_bf16 v[4:7], v[170:173], v[210:213], v[4:7]
	v_mfma_f32_16x16x32_bf16 v[0:3], v[178:181], v[210:213], v[0:3]
	s_setprio 0
	s_barrier
	s_add_i32 s59, 0, 0x18000
	s_add_i32 s60, 0, 0x1c000
	v_add_u32_e32 v132, s59, v163
	v_add_u32_e32 v169, s60, v163
	ds_read_b128 v[116:119], v132
	ds_read_b128 v[124:127], v132 offset:1024
	ds_read_b128 v[128:131], v132 offset:2048
	ds_read_b128 v[132:135], v132 offset:3072
	ds_read_b128 v[156:159], v169
	ds_read_b128 v[170:173], v169 offset:1024
	ds_read_b128 v[174:177], v169 offset:2048
	ds_read_b128 v[178:181], v169 offset:3072
	v_lshl_add_u64 v[216:217], s[36:37], 0, v[144:145]
	s_add_u32 s36, s36, 0x80000
	s_addc_u32 s37, s37, 0
	s_mov_b32 m0, s29
	v_lshl_add_u64 v[220:221], s[36:37], 0, v[144:145]
	ds_read_b128 v[182:185], v167 offset:32768
	ds_read_b128 v[186:189], v167 offset:33792
	ds_read_b128 v[190:193], v167 offset:34816
	ds_read_b128 v[194:197], v167 offset:35840
	ds_read_b128 v[198:201], v167 offset:36864
	ds_read_b128 v[202:205], v167 offset:37888
	ds_read_b128 v[206:209], v167 offset:38912
	ds_read_b128 v[210:213], v167 offset:39936
	global_load_lds_dwordx4 v[216:217], off
	s_mov_b32 m0, s41
	s_nop 0
	global_load_lds_dwordx4 v[218:219], off
	s_mov_b32 m0, s42
	s_nop 0
	global_load_lds_dwordx4 v[220:221], off
	v_lshl_add_u64 v[220:221], s[36:37], 0, v[146:147]
	s_mov_b32 m0, s43
	s_nop 0
	global_load_lds_dwordx4 v[220:221], off
	s_waitcnt vmcnt(8)
	s_waitcnt lgkmcnt(0)
	s_barrier
; #define PG8_STAGE(bufoff, gbase, voff) do { _Pragma("unroll") for (int _i = 0; _i < 2; ++_i) \
;         __builtin_amdgcn_global_load_lds((const unsigned*)((const char*)(gbase) + (voff)[_i]), (PG8_LAS unsigned*)(lds + (bufoff) + ldsw + _i * 8192), 16, 0, 0); } while (0)
; #define PG8_LDA(dst, b, h) do { _Pragma("unroll") for (int m = 0; m < 4; ++m) _Pragma("unroll") for (int k = 0; k < 2; ++k) dst[m][k] = *(const PG8_LAS bf16x8*)(lds + PG8_SA(b, h) + aoff + m * 2048 + k * 1024); } while (0)
; #define PG8_LDB(dst, b, h) do { _Pragma("unroll") for (int n = 0; n < 2; ++n) _Pragma("unroll") for (int k = 0; k < 2; ++k) dst[n][k] = *(const PG8_LAS bf16x8*)(lds + PG8_SB(b, h) + boff + n * 2048 + k * 1024); } while (0)
; #define PG8_MMA(ai, bj, At, Bt) do { __builtin_amdgcn_s_setprio(1); _Pragma("unroll") for (int m = 0; m < 4; ++m) _Pragma("unroll") for (int n = 0; n < 2; ++n) _Pragma("unroll") for (int k = 0; k < 2; ++k) \
;         acc[ai][bj][m][n] = __builtin_amdgcn_mfma_f32_16x16x32_bf16(Bt[n][k], At[m][k], acc[ai][bj][m][n], 0, 0, 0); __builtin_amdgcn_s_setprio(0); } while (0)
; template <class Epi, class Sched, bool ALIGN_EPI = false, bool SP2 = false>
; __device__ __forceinline__ void gemm_phase(PG8_LAS unsigned char* lds, const Gemm g, const Sched& S, const Epi& E) {
;     ...
;         for (int t = 0; t < nt; t += 2) {
;     ...
;             PG8_LDB(B0, 0, 0); PG8_LDB(B1, 0, 1); PG8_SCHED; PG8_LDA(At, 0, 0); PG8_STAGE(PG8_SA(1, 1), a1 + hstep, voffA);
;             PG8_WAIT_V(8); PG8_WAIT_L(0); PG8_BAR; PG8_MMA(0, 0, At, B0); PG8_MMA(0, 1, At, B1); PG8_BAR; PG8_SCHED;
;             PG8_LDA(At, 0, 1); PG8_STAGE(PG8_SB(0, 0), b2, voffB); PG8_STAGE(PG8_SB(0, 1), b2 + hstep, voffB); PG8_STAGE(PG8_SA(0, 0), a2, voffA);
;             PG8_WAIT_V(8); PG8_WAIT_L(0); PG8_BAR; PG8_MMA(1, 0, At, B0); PG8_MMA(1, 1, At, B1); PG8_BAR; PG8_SCHED;
;             PG8_LDB(B0, 1, 0); PG8_LDB(B1, 1, 1); PG8_SCHED; PG8_LDA(At, 1, 0); PG8_STAGE(PG8_SA(0, 1), a2 + hstep, voffA);
;             PG8_WAIT_V(8); PG8_WAIT_L(0); PG8_BAR; PG8_MMA(0, 0, At, B0); PG8_MMA(0, 1, At, B1); PG8_BAR; PG8_SCHED;
;             PG8_LDA(At, 1, 1); PG8_STAGE(PG8_SB(1, 0), b3, voffB); PG8_STAGE(PG8_SB(1, 1), b3 + hstep, voffB); PG8_STAGE(PG8_SA(1, 0), a3, voffA);
;             PG8_WAIT_V(8); PG8_WAIT_L(0); PG8_BAR; PG8_MMA(1, 0, At, B0); PG8_MMA(1, 1, At, B1); PG8_BAR; PG8_SCHED;
	s_setprio 1
	s_waitcnt lgkmcnt(0)
	v_mfma_f32_16x16x32_bf16 v[140:143], v[116:119], v[182:185], v[140:143]
	v_mfma_f32_16x16x32_bf16 v[136:139], v[128:131], v[182:185], v[136:139]
	v_mfma_f32_16x16x32_bf16 v[108:111], v[116:119], v[190:193], v[108:111]
	v_mfma_f32_16x16x32_bf16 v[104:107], v[128:131], v[190:193], v[104:107]
	v_mfma_f32_16x16x32_bf16 v[92:95], v[116:119], v[198:201], v[92:95]
	v_mfma_f32_16x16x32_bf16 v[88:91], v[128:131], v[198:201], v[88:91]
	v_mfma_f32_16x16x32_bf16 v[76:79], v[116:119], v[206:209], v[76:79]
	v_mfma_f32_16x16x32_bf16 v[72:75], v[128:131], v[206:209], v[72:75]
	v_mfma_f32_16x16x32_bf16 v[140:143], v[124:127], v[186:189], v[140:143]
	v_mfma_f32_16x16x32_bf16 v[136:139], v[132:135], v[186:189], v[136:139]
	v_mfma_f32_16x16x32_bf16 v[108:111], v[124:127], v[194:197], v[108:111]
	v_mfma_f32_16x16x32_bf16 v[104:107], v[132:135], v[194:197], v[104:107]
	v_mfma_f32_16x16x32_bf16 v[92:95], v[124:127], v[202:205], v[92:95]
	v_mfma_f32_16x16x32_bf16 v[88:91], v[132:135], v[202:205], v[88:91]
	v_mfma_f32_16x16x32_bf16 v[76:79], v[124:127], v[210:213], v[76:79]
	v_mfma_f32_16x16x32_bf16 v[72:75], v[132:135], v[210:213], v[72:75]
	s_setprio 0
	s_setprio 1
	v_mfma_f32_16x16x32_bf16 v[120:123], v[156:159], v[182:185], v[120:123]
	v_mfma_f32_16x16x32_bf16 v[112:115], v[174:177], v[182:185], v[112:115]
	v_mfma_f32_16x16x32_bf16 v[100:103], v[156:159], v[190:193], v[100:103]
	v_mfma_f32_16x16x32_bf16 v[96:99], v[174:177], v[190:193], v[96:99]
	v_mfma_f32_16x16x32_bf16 v[84:87], v[156:159], v[198:201], v[84:87]
	v_mfma_f32_16x16x32_bf16 v[80:83], v[174:177], v[198:201], v[80:83]
	v_mfma_f32_16x16x32_bf16 v[68:71], v[156:159], v[206:209], v[68:71]
	v_mfma_f32_16x16x32_bf16 v[64:67], v[174:177], v[206:209], v[64:67]
	v_mfma_f32_16x16x32_bf16 v[120:123], v[170:173], v[186:189], v[120:123]
	v_mfma_f32_16x16x32_bf16 v[112:115], v[178:181], v[186:189], v[112:115]
	v_mfma_f32_16x16x32_bf16 v[100:103], v[170:173], v[194:197], v[100:103]
	v_mfma_f32_16x16x32_bf16 v[96:99], v[178:181], v[194:197], v[96:99]
	v_mfma_f32_16x16x32_bf16 v[84:87], v[170:173], v[202:205], v[84:87]
	v_mfma_f32_16x16x32_bf16 v[80:83], v[178:181], v[202:205], v[80:83]
	v_mfma_f32_16x16x32_bf16 v[68:71], v[170:173], v[210:213], v[68:71]
	v_mfma_f32_16x16x32_bf16 v[64:67], v[178:181], v[210:213], v[64:67]
	s_setprio 0
	s_barrier
	s_add_i32 s36, s59, s40
	v_lshl_add_u64 v[160:161], v[160:161], 0, s[10:11]
	s_mov_b32 m0, s36
	ds_read_b128 v[182:185], v167 offset:49152
	ds_read_b128 v[186:189], v167 offset:50176
	ds_read_b128 v[190:193], v167 offset:51200
	ds_read_b128 v[194:197], v167 offset:52224
	ds_read_b128 v[198:201], v167 offset:53248
	ds_read_b128 v[202:205], v167 offset:54272
	ds_read_b128 v[206:209], v167 offset:55296
	ds_read_b128 v[210:213], v167 offset:56320
	global_load_lds_dwordx4 v[160:161], off
	s_add_i32 m0, s36, 0x2000
	s_add_u32 s34, s34, 0x80080
	v_lshl_add_u64 v[160:161], v[214:215], 0, s[10:11]
	s_addc_u32 s35, s35, 0
	s_add_i32 s36, s60, s40
	global_load_lds_dwordx4 v[160:161], off
	v_lshl_add_u64 v[160:161], s[34:35], 0, v[144:145]
	s_mov_b32 m0, s36
	s_nop 0
	global_load_lds_dwordx4 v[160:161], off
	v_lshl_add_u64 v[160:161], s[34:35], 0, v[146:147]
	s_add_i32 m0, s36, 0x2000
	s_nop 0
	global_load_lds_dwordx4 v[160:161], off
	s_waitcnt vmcnt(6)
	s_waitcnt lgkmcnt(0)
	s_barrier
	s_setprio 1
	s_waitcnt lgkmcnt(0)
	v_mfma_f32_16x16x32_bf16 v[60:63], v[116:119], v[182:185], v[60:63]
	v_mfma_f32_16x16x32_bf16 v[56:59], v[128:131], v[182:185], v[56:59]
	v_mfma_f32_16x16x32_bf16 v[44:47], v[116:119], v[190:193], v[44:47]
	v_mfma_f32_16x16x32_bf16 v[40:43], v[128:131], v[190:193], v[40:43]
	v_mfma_f32_16x16x32_bf16 v[28:31], v[116:119], v[198:201], v[28:31]
	v_mfma_f32_16x16x32_bf16 v[24:27], v[128:131], v[198:201], v[24:27]
	v_mfma_f32_16x16x32_bf16 v[12:15], v[116:119], v[206:209], v[12:15]
	v_mfma_f32_16x16x32_bf16 v[8:11], v[128:131], v[206:209], v[8:11]
	v_mfma_f32_16x16x32_bf16 v[60:63], v[124:127], v[186:189], v[60:63]
	v_mfma_f32_16x16x32_bf16 v[56:59], v[132:135], v[186:189], v[56:59]
	v_mfma_f32_16x16x32_bf16 v[44:47], v[124:127], v[194:197], v[44:47]
	v_mfma_f32_16x16x32_bf16 v[40:43], v[132:135], v[194:197], v[40:43]
	v_mfma_f32_16x16x32_bf16 v[28:31], v[124:127], v[202:205], v[28:31]
	v_mfma_f32_16x16x32_bf16 v[24:27], v[132:135], v[202:205], v[24:27]
	v_mfma_f32_16x16x32_bf16 v[12:15], v[124:127], v[210:213], v[12:15]
	v_mfma_f32_16x16x32_bf16 v[8:11], v[132:135], v[210:213], v[8:11]
	s_setprio 0
	s_setprio 1
	v_mfma_f32_16x16x32_bf16 v[52:55], v[156:159], v[182:185], v[52:55]
	v_mfma_f32_16x16x32_bf16 v[48:51], v[174:177], v[182:185], v[48:51]
	v_mfma_f32_16x16x32_bf16 v[36:39], v[156:159], v[190:193], v[36:39]
	v_mfma_f32_16x16x32_bf16 v[32:35], v[174:177], v[190:193], v[32:35]
	v_mfma_f32_16x16x32_bf16 v[20:23], v[156:159], v[198:201], v[20:23]
	v_mfma_f32_16x16x32_bf16 v[16:19], v[174:177], v[198:201], v[16:19]
	v_mfma_f32_16x16x32_bf16 v[4:7], v[156:159], v[206:209], v[4:7]
	v_mfma_f32_16x16x32_bf16 v[0:3], v[174:177], v[206:209], v[0:3]
	v_mfma_f32_16x16x32_bf16 v[52:55], v[170:173], v[186:189], v[52:55]
	v_mfma_f32_16x16x32_bf16 v[48:51], v[178:181], v[186:189], v[48:51]
	v_mfma_f32_16x16x32_bf16 v[36:39], v[170:173], v[194:197], v[36:39]
	v_mfma_f32_16x16x32_bf16 v[32:35], v[178:181], v[194:197], v[32:35]
	v_mfma_f32_16x16x32_bf16 v[20:23], v[170:173], v[202:205], v[20:23]
	v_mfma_f32_16x16x32_bf16 v[16:19], v[178:181], v[202:205], v[16:19]
	v_mfma_f32_16x16x32_bf16 v[4:7], v[170:173], v[210:213], v[4:7]
	v_mfma_f32_16x16x32_bf16 v[0:3], v[178:181], v[210:213], v[0:3]
	s_setprio 0
	s_barrier
	s_add_i32 s58, s58, 2
	s_add_u32 s30, s30, 0x100
	s_addc_u32 s31, s31, 0
	s_add_u32 s56, s56, 0x100
	s_addc_u32 s57, s57, 0
	s_cmp_gt_u32 s58, 29
	s_cbranch_scc0 .LBB0_1073
	s_and_b64 vcc, exec, s[12:13]
	s_cbranch_vccz .LBB0_1076
	s_barrier
